# code placement: the five GEMM K-loop heads aligned to 64 bytes (p2align 6)
# speedup vs baseline: 1.0003x; 1.0003x over previous
; template <class Epi, int AMODE>
; __device__ __forceinline__ void gemm_phase(LAS unsigned char* lds, const Gemm g, const StaticOrder& S, const Epi& E, int stagger_us, int tid_in) {
;     ...
;         const bool has_next = S.next(ui + 1, nxt);
;         const char* nA = has_next ? Abase + (size_t)nxt.pm * tstepA : cA; const char* nB = has_next ? (const char*)g.Bt + (size_t)nxt.pn * tstepB : cB;
;         for (int t = 0; t < nt; t += 2) {
;             const bool last = (t == nt - 2);
;             const char* a1 = cA + (size_t)(t + 1) * kstep;
;             const char* a2 = last ? nA : cA + (size_t)(t + 2) * kstep; const char* b2 = last ? nB : cB + (size_t)(t + 2) * kstep;
;             const char* a3 = a2 + kstep; const char* b3 = b2 + kstep;
;     ...
;         for (int a = 0; a < 2; ++a)
; #pragma unroll
;             for (int b = 0; b < 2; ++b)
; #pragma unroll
;                 for (int m = 0; m < 4; ++m)
; #pragma unroll
;                     for (int n = 0; n < 2; ++n) acc[a][b][m][n] = (f32x4){0.f, 0.f, 0.f, 0.f};
.LBB0_395:
	s_ashr_i32 s51, s50, 31
	s_lshl_b64 s[28:29], s[50:51], 20
	s_add_u32 s52, s67, s28
	s_addc_u32 s53, s69, s29
	s_and_b64 s[28:29], s[36:37], exec
	s_cselect_b32 s27, s53, s7
	s_cselect_b32 s28, s52, s6
	s_ashr_i32 s49, s48, 31
	s_lshl_b64 s[30:31], s[48:49], 20
	s_add_u32 s54, s24, s30
	s_addc_u32 s55, s25, s31
	s_and_b64 s[30:31], s[36:37], exec
	s_cselect_b32 s49, s55, s5
	s_cselect_b32 s51, s54, s4
	s_add_u32 s60, s6, 0x80080
	s_addc_u32 s61, s7, 0
	s_add_u32 vcc_lo, s4, 0x100
	v_mov_b32_e32 v2, 0
	s_addc_u32 vcc_hi, s5, 0
	s_mov_b32 s29, -2
	v_mov_b32_e32 v3, v2
	v_mov_b32_e32 v4, v2
	v_mov_b32_e32 v5, v2
	v_mov_b32_e32 v6, v2
	v_mov_b32_e32 v7, v2
	v_mov_b32_e32 v8, v2
	v_mov_b32_e32 v9, v2
	v_mov_b32_e32 v18, v2
	v_mov_b32_e32 v19, v2
	v_mov_b32_e32 v20, v2
	v_mov_b32_e32 v21, v2
	v_mov_b32_e32 v22, v2
	v_mov_b32_e32 v23, v2
	v_mov_b32_e32 v24, v2
	v_mov_b32_e32 v25, v2
	v_mov_b32_e32 v34, v2
	v_mov_b32_e32 v35, v2
	v_mov_b32_e32 v36, v2
	v_mov_b32_e32 v37, v2
	v_mov_b32_e32 v38, v2
	v_mov_b32_e32 v39, v2
	v_mov_b32_e32 v40, v2
	v_mov_b32_e32 v41, v2
	v_mov_b32_e32 v50, v2
	v_mov_b32_e32 v51, v2
	v_mov_b32_e32 v52, v2
	v_mov_b32_e32 v53, v2
	v_mov_b32_e32 v54, v2
	v_mov_b32_e32 v55, v2
	v_mov_b32_e32 v56, v2
	v_mov_b32_e32 v57, v2
	v_mov_b32_e32 v10, v2
	v_mov_b32_e32 v11, v2
	v_mov_b32_e32 v12, v2
	v_mov_b32_e32 v13, v2
	v_mov_b32_e32 v14, v2
	v_mov_b32_e32 v15, v2
	v_mov_b32_e32 v16, v2
	v_mov_b32_e32 v17, v2
	v_mov_b32_e32 v26, v2
	v_mov_b32_e32 v27, v2
	v_mov_b32_e32 v28, v2
	v_mov_b32_e32 v29, v2
	v_mov_b32_e32 v30, v2
	v_mov_b32_e32 v31, v2
	v_mov_b32_e32 v32, v2
	v_mov_b32_e32 v33, v2
	v_mov_b32_e32 v42, v2
	v_mov_b32_e32 v43, v2
	v_mov_b32_e32 v44, v2
	v_mov_b32_e32 v45, v2
	v_mov_b32_e32 v46, v2
	v_mov_b32_e32 v47, v2
	v_mov_b32_e32 v48, v2
	v_mov_b32_e32 v49, v2
	v_mov_b32_e32 v58, v2
	v_mov_b32_e32 v59, v2
	v_mov_b32_e32 v60, v2
	v_mov_b32_e32 v61, v2
	v_mov_b32_e32 v62, v2
	v_mov_b32_e32 v63, v2
	v_mov_b32_e32 v64, v2
	v_mov_b32_e32 v65, v2
	v_mov_b32_e32 v66, v2
	v_mov_b32_e32 v67, v2
	v_mov_b32_e32 v68, v2
	v_mov_b32_e32 v69, v2
	v_mov_b32_e32 v70, v2
	v_mov_b32_e32 v71, v2
	v_mov_b32_e32 v72, v2
	v_mov_b32_e32 v73, v2
	v_mov_b32_e32 v82, v2
	v_mov_b32_e32 v83, v2
	v_mov_b32_e32 v84, v2
	v_mov_b32_e32 v85, v2
	v_mov_b32_e32 v86, v2
	v_mov_b32_e32 v87, v2
	v_mov_b32_e32 v88, v2
	v_mov_b32_e32 v89, v2
	v_mov_b32_e32 v98, v2
	v_mov_b32_e32 v99, v2
	v_mov_b32_e32 v100, v2
	v_mov_b32_e32 v101, v2
	v_mov_b32_e32 v102, v2
	v_mov_b32_e32 v103, v2
	v_mov_b32_e32 v104, v2
	v_mov_b32_e32 v105, v2
	v_mov_b32_e32 v114, v2
	v_mov_b32_e32 v115, v2
	v_mov_b32_e32 v116, v2
	v_mov_b32_e32 v117, v2
	v_mov_b32_e32 v118, v2
	v_mov_b32_e32 v119, v2
	v_mov_b32_e32 v120, v2
	v_mov_b32_e32 v121, v2
	v_mov_b32_e32 v74, v2
	v_mov_b32_e32 v75, v2
	v_mov_b32_e32 v76, v2
	v_mov_b32_e32 v77, v2
	v_mov_b32_e32 v78, v2
	v_mov_b32_e32 v79, v2
	v_mov_b32_e32 v80, v2
	v_mov_b32_e32 v81, v2
	v_mov_b32_e32 v90, v2
	v_mov_b32_e32 v91, v2
	v_mov_b32_e32 v92, v2
	v_mov_b32_e32 v93, v2
	v_mov_b32_e32 v94, v2
	v_mov_b32_e32 v95, v2
	v_mov_b32_e32 v96, v2
	v_mov_b32_e32 v97, v2
	v_mov_b32_e32 v106, v2
	v_mov_b32_e32 v107, v2
	v_mov_b32_e32 v108, v2
	v_mov_b32_e32 v109, v2
	v_mov_b32_e32 v110, v2
	v_mov_b32_e32 v111, v2
	v_mov_b32_e32 v112, v2
	v_mov_b32_e32 v113, v2
	v_mov_b32_e32 v122, v2
	v_mov_b32_e32 v123, v2
	v_mov_b32_e32 v124, v2
	v_mov_b32_e32 v125, v2
	v_mov_b32_e32 v126, v2
	v_mov_b32_e32 v127, v2
	v_mov_b32_e32 v128, v2
	v_mov_b32_e32 v129, v2
	.p2align	6

; template <class Epi, int AMODE>
; __device__ __forceinline__ void gemm_phase(LAS unsigned char* lds, const Gemm g, const StaticOrder& S, const Epi& E, int stagger_us, int tid_in) {
;     ...
;         const bool has_next = S.next(ui + 1, nxt);
;         const char* nA = has_next ? Abase + (size_t)nxt.pm * tstepA : cA; const char* nB = has_next ? (const char*)g.Bt + (size_t)nxt.pn * tstepB : cB;
;         for (int t = 0; t < nt; t += 2) {
;             const bool last = (t == nt - 2);
;             const char* a1 = cA + (size_t)(t + 1) * kstep;
;             const char* a2 = last ? nA : cA + (size_t)(t + 2) * kstep; const char* b2 = last ? nB : cB + (size_t)(t + 2) * kstep;
;             const char* a3 = a2 + kstep; const char* b3 = b2 + kstep;
;     ...
;         for (int a = 0; a < 2; ++a)
; #pragma unroll
;             for (int b = 0; b < 2; ++b)
; #pragma unroll
;                 for (int m = 0; m < 4; ++m)
; #pragma unroll
;                     for (int n = 0; n < 2; ++n) acc[a][b][m][n] = (f32x4){0.f, 0.f, 0.f, 0.f};
.LBB0_1198:
	s_ashr_i32 s61, s60, 31
	s_lshl_b64 s[6:7], s[60:61], 20
	s_add_u32 s62, s24, s6
	s_addc_u32 s63, s25, s7
	s_and_b64 s[6:7], s[38:39], exec
	s_cselect_b32 s61, s63, s47
	s_cselect_b32 vcc_lo, s62, s46
	s_ashr_i32 s59, s58, 31
	s_lshl_b64 s[6:7], s[58:59], 20
	s_add_u32 s92, s9, s6
	s_addc_u32 s93, s12, s7
	s_and_b64 s[6:7], s[38:39], exec
	s_cselect_b32 s59, s93, s5
	s_cselect_b32 vcc_hi, s92, s4
	s_add_u32 s29, s4, 0x100
	v_mov_b32_e32 v2, 0
	s_addc_u32 s30, s5, 0
	s_mov_b32 s31, -2
	v_mov_b32_e32 v3, v2
	v_mov_b32_e32 v4, v2
	v_mov_b32_e32 v5, v2
	v_mov_b32_e32 v6, v2
	v_mov_b32_e32 v7, v2
	v_mov_b32_e32 v8, v2
	v_mov_b32_e32 v9, v2
	v_mov_b32_e32 v18, v2
	v_mov_b32_e32 v19, v2
	v_mov_b32_e32 v20, v2
	v_mov_b32_e32 v21, v2
	v_mov_b32_e32 v22, v2
	v_mov_b32_e32 v23, v2
	v_mov_b32_e32 v24, v2
	v_mov_b32_e32 v25, v2
	v_mov_b32_e32 v34, v2
	v_mov_b32_e32 v35, v2
	v_mov_b32_e32 v36, v2
	v_mov_b32_e32 v37, v2
	v_mov_b32_e32 v38, v2
	v_mov_b32_e32 v39, v2
	v_mov_b32_e32 v40, v2
	v_mov_b32_e32 v41, v2
	v_mov_b32_e32 v66, v2
	v_mov_b32_e32 v67, v2
	v_mov_b32_e32 v68, v2
	v_mov_b32_e32 v69, v2
	v_mov_b32_e32 v70, v2
	v_mov_b32_e32 v71, v2
	v_mov_b32_e32 v72, v2
	v_mov_b32_e32 v73, v2
	v_mov_b32_e32 v10, v2
	v_mov_b32_e32 v11, v2
	v_mov_b32_e32 v12, v2
	v_mov_b32_e32 v13, v2
	v_mov_b32_e32 v14, v2
	v_mov_b32_e32 v15, v2
	v_mov_b32_e32 v16, v2
	v_mov_b32_e32 v17, v2
	v_mov_b32_e32 v26, v2
	v_mov_b32_e32 v27, v2
	v_mov_b32_e32 v28, v2
	v_mov_b32_e32 v29, v2
	v_mov_b32_e32 v30, v2
	v_mov_b32_e32 v31, v2
	v_mov_b32_e32 v32, v2
	v_mov_b32_e32 v33, v2
	v_mov_b32_e32 v42, v2
	v_mov_b32_e32 v43, v2
	v_mov_b32_e32 v44, v2
	v_mov_b32_e32 v45, v2
	v_mov_b32_e32 v46, v2
	v_mov_b32_e32 v47, v2
	v_mov_b32_e32 v48, v2
	v_mov_b32_e32 v49, v2
	v_mov_b32_e32 v74, v2
	v_mov_b32_e32 v75, v2
	v_mov_b32_e32 v76, v2
	v_mov_b32_e32 v77, v2
	v_mov_b32_e32 v78, v2
	v_mov_b32_e32 v79, v2
	v_mov_b32_e32 v80, v2
	v_mov_b32_e32 v81, v2
	v_mov_b32_e32 v82, v2
	v_mov_b32_e32 v83, v2
	v_mov_b32_e32 v84, v2
	v_mov_b32_e32 v85, v2
	v_mov_b32_e32 v86, v2
	v_mov_b32_e32 v87, v2
	v_mov_b32_e32 v88, v2
	v_mov_b32_e32 v89, v2
	v_mov_b32_e32 v98, v2
	v_mov_b32_e32 v99, v2
	v_mov_b32_e32 v100, v2
	v_mov_b32_e32 v101, v2
	v_mov_b32_e32 v102, v2
	v_mov_b32_e32 v103, v2
	v_mov_b32_e32 v104, v2
	v_mov_b32_e32 v105, v2
	v_mov_b32_e32 v114, v2
	v_mov_b32_e32 v115, v2
	v_mov_b32_e32 v116, v2
	v_mov_b32_e32 v117, v2
	v_mov_b32_e32 v118, v2
	v_mov_b32_e32 v119, v2
	v_mov_b32_e32 v120, v2
	v_mov_b32_e32 v121, v2
	s_waitcnt vmcnt(0)
	v_mov_b32_e32 v130, v2
	v_mov_b32_e32 v131, v2
	v_mov_b32_e32 v132, v2
	v_mov_b32_e32 v133, v2
	v_mov_b32_e32 v134, v2
	v_mov_b32_e32 v135, v2
	v_mov_b32_e32 v136, v2
	v_mov_b32_e32 v137, v2
	v_mov_b32_e32 v90, v2
	v_mov_b32_e32 v91, v2
	v_mov_b32_e32 v92, v2
	v_mov_b32_e32 v93, v2
	v_mov_b32_e32 v94, v2
	v_mov_b32_e32 v95, v2
	v_mov_b32_e32 v96, v2
	v_mov_b32_e32 v97, v2
	v_mov_b32_e32 v106, v2
	v_mov_b32_e32 v107, v2
	v_mov_b32_e32 v108, v2
	v_mov_b32_e32 v109, v2
	v_mov_b32_e32 v110, v2
	v_mov_b32_e32 v111, v2
	v_mov_b32_e32 v112, v2
	v_mov_b32_e32 v113, v2
	v_mov_b32_e32 v122, v2
	v_mov_b32_e32 v123, v2
	v_mov_b32_e32 v124, v2
	v_mov_b32_e32 v125, v2
	v_mov_b32_e32 v126, v2
	v_mov_b32_e32 v127, v2
	v_mov_b32_e32 v128, v2
	v_mov_b32_e32 v129, v2
	v_mov_b32_e32 v138, v2
	v_mov_b32_e32 v139, v2
	v_mov_b32_e32 v140, v2
	v_mov_b32_e32 v141, v2
	v_mov_b32_e32 v142, v2
	v_mov_b32_e32 v143, v2
	v_mov_b32_e32 v144, v2
	v_mov_b32_e32 v145, v2
	.p2align	6

; #define PG8_STAGE(bufoff, gbase, voff) do { _Pragma("unroll") for (int _i = 0; _i < 2; ++_i) \
;         __builtin_amdgcn_global_load_lds((const unsigned*)((const char*)(gbase) + (voff)[_i]), (LAS unsigned*)(lds + (bufoff) + ldsw + _i * 8192), 16, 0, 0); } while (0)
; #define PG8_LDA(dst, b, h) do { _Pragma("unroll") for (int m = 0; m < 4; ++m) _Pragma("unroll") for (int k = 0; k < 2; ++k) dst[m][k] = *(const LAS bf16x8*)(lds + PG8_SA(b, h) + aoff + m * 2048 + k * 1024); } while (0)
; #define PG8_LDB(dst, b, h) do { _Pragma("unroll") for (int n = 0; n < 2; ++n) _Pragma("unroll") for (int k = 0; k < 2; ++k) dst[n][k] = *(const LAS bf16x8*)(lds + PG8_SB(b, h) + boff + n * 2048 + k * 1024); } while (0)
; #define PG8_WAIT_V(n) asm volatile("s_waitcnt vmcnt(" #n ")" ::: "memory")
; #define PG8_WAIT_L(n) asm volatile("s_waitcnt lgkmcnt(" #n ")" ::: "memory")
; #define PG8_BAR __builtin_amdgcn_s_barrier()
; #define PG8_SCHED __builtin_amdgcn_sched_barrier(0)
; template <class Epi, int AMODE>
; __device__ __forceinline__ void gemm_phase(LAS unsigned char* lds, const Gemm g, const StaticOrder& S, const Epi& E, int stagger_us, int tid_in) {
;     ...
;             PG8_LDB(B0, 0, 0); PG8_LDB(B1, 0, 1); PG8_SCHED; PG8_LDA(At, 0, 0); PG8_STAGE(PG8_SA(1, 1), a1 + hstepA, voffA);
;             PG8_WAIT_V(8); PG8_WAIT_L(0); PG8_BAR; PG8_MMA(0, 0, At, B0); PG8_MMA(0, 1, At, B1); PG8_BAR; PG8_SCHED;
;     __device__ __forceinline__ void operator()(f32x4 (&acc)[2][2][4][2], const Unit& u, int wr, int wc, int fr, int fq) const {
;     ...
;         const int tok0 = 252 * u.pm + 126 * wr - 1;
;         {
;             const int tq = tok0 + 8 * fr; const int tA = tq < 0 ? 0 : (tq > TOK - 1 ? TOK - 1 : tq), tB = (tq + 7) > TOK - 1 ? TOK - 1 : (tq + 7);
;             const int bA = batch_of(tA), bB = batch_of(tB); const bool same = __all(bA == bB);
;             const float* bp0 = bias + 256 * u.pn + 32 * wc + 8 * fq;
;             f32x4 bvA[2][2]; float sq[8];
; #pragma unroll
;             for (int am = 0; am < 8; ++am) { int tok = tq + am; tok = tok < 0 ? 0 : (tok > TOK - 1 ? TOK - 1 : tok); sq[am] = LDG(float, ssq + tok); }
; #pragma unroll
;             for (int bj = 0; bj < 2; ++bj)
; #pragma unroll
;                 for (int n = 0; n < 2; ++n) bvA[bj][n] = LDG(f32x4, bp0 + (size_t)bA * (2 * DFF) + bj * HALF + 4 * n);
.LBB0_1298:
	s_ashr_i32 s47, s46, 31
	s_lshl_b64 s[6:7], s[46:47], 20
	s_add_u32 s96, s9, s6
	s_addc_u32 s97, s72, s7
	s_and_b64 s[6:7], s[42:43], exec
	s_cselect_b32 s27, s97, s5
	s_cselect_b32 s28, s96, s4
	s_add_u32 s29, s4, 0x100
	v_mov_b32_e32 v2, 0
	s_addc_u32 s30, s5, 0
	s_mov_b32 s31, -2
	s_mul_i32 s6, s26, 0xfc
	v_add_u32_e32 v222, s6, v197
	v_med3_i32 v240, v222, 0, v238
	v_add_u32_e32 v241, 0xffffe000, v240
	v_lshrrev_b32_e32 v241, 12, v241
	v_add_u32_e32 v241, 4, v241
	v_lshrrev_b32_e32 v242, 11, v240
	v_mov_b32_e32 v243, 0x2000
	v_cmp_gt_i32_e64 s[6:7], v243, v222
	s_nop 1
	v_cndmask_b32_e64 v241, v241, v242, s[6:7]
	s_lshl_b32 s6, s92, 8
	s_ashr_i32 s7, s6, 31
	v_lshl_add_u64 v[236:237], s[6:7], 2, v[184:185]
	v_mad_u64_u32 v[236:237], s[6:7], v241, s15, v[236:237]
	v_med3_i32 v224, v222, 0, v238
	v_lshlrev_b32_e32 v224, 2, v224
	global_load_dword v224, v224, s[56:57]
	v_add_u32_e32 v228, 1, v222
	v_med3_i32 v228, v228, 0, v238
	v_lshlrev_b32_e32 v228, 2, v228
	global_load_dword v228, v228, s[56:57]
	v_add_u32_e32 v231, 2, v222
	v_med3_i32 v231, v231, 0, v238
	v_lshlrev_b32_e32 v231, 2, v231
	global_load_dword v231, v231, s[56:57]
	v_add_u32_e32 v233, 3, v222
	v_med3_i32 v233, v233, 0, v238
	v_lshlrev_b32_e32 v233, 2, v233
	global_load_dword v233, v233, s[56:57]
	v_add_u32_e32 v234, 4, v222
	v_med3_i32 v234, v234, 0, v238
	v_lshlrev_b32_e32 v234, 2, v234
	global_load_dword v234, v234, s[56:57]
	v_add_u32_e32 v239, 5, v222
	v_med3_i32 v239, v239, 0, v238
	v_lshlrev_b32_e32 v239, 2, v239
	global_load_dword v239, v239, s[56:57]
	v_add_u32_e32 v252, 6, v222
	v_med3_i32 v252, v252, 0, v238
	v_lshlrev_b32_e32 v252, 2, v252
	global_load_dword v252, v252, s[56:57]
	v_add_u32_e32 v253, 7, v222
	v_med3_i32 v253, v253, 0, v238
	v_lshlrev_b32_e32 v253, 2, v253
	global_load_dword v253, v253, s[56:57]
	global_load_dwordx4 v[240:243], v[236:237], off
	global_load_dwordx4 v[244:247], v[236:237], off offset:16
	global_load_dwordx4 v[248:251], v[236:237], off offset:512
	global_load_dwordx2 v[222:223], v[236:237], off offset:528
	s_nop 0
	global_load_dwordx2 v[236:237], v[236:237], off offset:536
	v_mov_b32_e32 v3, v2
	v_mov_b32_e32 v4, v2
	v_mov_b32_e32 v5, v2
	v_mov_b32_e32 v14, v2
	v_mov_b32_e32 v15, v2
	v_mov_b32_e32 v16, v2
	v_mov_b32_e32 v17, v2
	v_mov_b32_e32 v10, v2
	v_mov_b32_e32 v11, v2
	v_mov_b32_e32 v12, v2
	v_mov_b32_e32 v13, v2
	v_mov_b32_e32 v26, v2
	v_mov_b32_e32 v27, v2
	v_mov_b32_e32 v28, v2
	v_mov_b32_e32 v29, v2
	v_mov_b32_e32 v6, v2
	v_mov_b32_e32 v7, v2
	v_mov_b32_e32 v8, v2
	v_mov_b32_e32 v9, v2
	v_mov_b32_e32 v42, v2
	v_mov_b32_e32 v43, v2
	v_mov_b32_e32 v44, v2
	v_mov_b32_e32 v45, v2
	v_mov_b32_e32 v30, v2
	v_mov_b32_e32 v31, v2
	v_mov_b32_e32 v32, v2
	v_mov_b32_e32 v33, v2
	v_mov_b32_e32 v58, v2
	v_mov_b32_e32 v59, v2
	v_mov_b32_e32 v60, v2
	v_mov_b32_e32 v61, v2
	v_mov_b32_e32 v74, v2
	v_mov_b32_e32 v75, v2
	v_mov_b32_e32 v76, v2
	v_mov_b32_e32 v77, v2
	v_mov_b32_e32 v22, v2
	v_mov_b32_e32 v23, v2
	v_mov_b32_e32 v24, v2
	v_mov_b32_e32 v25, v2
	v_mov_b32_e32 v34, v2
	v_mov_b32_e32 v35, v2
	v_mov_b32_e32 v36, v2
	v_mov_b32_e32 v37, v2
	v_mov_b32_e32 v18, v2
	v_mov_b32_e32 v19, v2
	v_mov_b32_e32 v20, v2
	v_mov_b32_e32 v21, v2
	v_mov_b32_e32 v50, v2
	v_mov_b32_e32 v51, v2
	v_mov_b32_e32 v52, v2
	v_mov_b32_e32 v53, v2
	v_mov_b32_e32 v38, v2
	v_mov_b32_e32 v39, v2
	v_mov_b32_e32 v40, v2
	v_mov_b32_e32 v41, v2
	v_mov_b32_e32 v46, v2
	v_mov_b32_e32 v47, v2
	v_mov_b32_e32 v48, v2
	v_mov_b32_e32 v49, v2
	v_mov_b32_e32 v54, v2
	v_mov_b32_e32 v55, v2
	v_mov_b32_e32 v56, v2
	v_mov_b32_e32 v57, v2
	v_mov_b32_e32 v66, v2
	v_mov_b32_e32 v67, v2
	v_mov_b32_e32 v68, v2
	v_mov_b32_e32 v69, v2
	v_mov_b32_e32 v78, v2
	v_mov_b32_e32 v79, v2
	v_mov_b32_e32 v80, v2
	v_mov_b32_e32 v81, v2
	v_mov_b32_e32 v62, v2
	v_mov_b32_e32 v63, v2
	v_mov_b32_e32 v64, v2
	v_mov_b32_e32 v65, v2
	v_mov_b32_e32 v70, v2
	v_mov_b32_e32 v71, v2
	v_mov_b32_e32 v72, v2
	v_mov_b32_e32 v73, v2
	v_mov_b32_e32 v86, v2
	v_mov_b32_e32 v87, v2
	v_mov_b32_e32 v88, v2
	v_mov_b32_e32 v89, v2
	v_mov_b32_e32 v94, v2
	v_mov_b32_e32 v95, v2
	v_mov_b32_e32 v96, v2
	v_mov_b32_e32 v97, v2
	v_mov_b32_e32 v98, v2
	v_mov_b32_e32 v99, v2
	v_mov_b32_e32 v100, v2
	v_mov_b32_e32 v101, v2
	v_mov_b32_e32 v106, v2
	v_mov_b32_e32 v107, v2
	v_mov_b32_e32 v108, v2
	v_mov_b32_e32 v109, v2
	v_mov_b32_e32 v82, v2
	v_mov_b32_e32 v83, v2
	v_mov_b32_e32 v84, v2
	v_mov_b32_e32 v85, v2
	v_mov_b32_e32 v90, v2
	v_mov_b32_e32 v91, v2
	v_mov_b32_e32 v92, v2
	v_mov_b32_e32 v93, v2
	v_mov_b32_e32 v102, v2
	v_mov_b32_e32 v103, v2
	v_mov_b32_e32 v104, v2
	v_mov_b32_e32 v105, v2
	v_mov_b32_e32 v110, v2
	v_mov_b32_e32 v111, v2
	v_mov_b32_e32 v112, v2
	v_mov_b32_e32 v113, v2
	v_mov_b32_e32 v114, v2
	v_mov_b32_e32 v115, v2
	v_mov_b32_e32 v116, v2
	v_mov_b32_e32 v117, v2
	v_mov_b32_e32 v118, v2
	v_mov_b32_e32 v119, v2
	v_mov_b32_e32 v120, v2
	v_mov_b32_e32 v121, v2
	v_mov_b32_e32 v122, v2
	v_mov_b32_e32 v123, v2
	v_mov_b32_e32 v124, v2
	v_mov_b32_e32 v125, v2
	v_mov_b32_e32 v126, v2
	v_mov_b32_e32 v127, v2
	v_mov_b32_e32 v128, v2
	v_mov_b32_e32 v129, v2
	s_add_u32 s4, s44, 0x100
	s_addc_u32 s5, s45, 0
	s_add_i32 s34, 0, 0x10000
	s_cmp_eq_u32 s31, 28
	s_cselect_b32 s43, s95, s5
	s_cselect_b32 s42, s94, s4
	s_cselect_b32 s7, s27, s30
	s_cselect_b32 s6, s28, s29
	s_add_i32 s35, 0, 0x14000
	v_add_u32_e32 v142, s34, v196
	v_add_u32_e32 v158, s35, v196
	ds_read_b128 v[130:133], v142
	ds_read_b128 v[134:137], v142 offset:1024
	ds_read_b128 v[138:141], v142 offset:2048
	ds_read_b128 v[142:145], v142 offset:3072
	ds_read_b128 v[146:149], v158
	ds_read_b128 v[150:153], v158 offset:1024
	ds_read_b128 v[154:157], v158 offset:2048
	ds_read_b128 v[158:161], v158 offset:3072
	v_lshl_add_u64 v[194:195], s[44:45], 0, v[186:187]
	s_add_i32 m0, s93, 0xc000
	ds_read_b128 v[162:165], v201
	ds_read_b128 v[166:169], v201 offset:1024
	ds_read_b128 v[170:173], v201 offset:2048
	ds_read_b128 v[174:177], v201 offset:3072
	ds_read_b128 v[190:193], v201 offset:4096
	ds_read_b128 v[202:205], v201 offset:5120
	ds_read_b128 v[206:209], v201 offset:6144
	ds_read_b128 v[210:213], v201 offset:7168
	global_load_lds_dwordx4 v[194:195], off
	s_add_i32 m0, s93, 0xe000
	v_lshl_add_u64 v[194:195], s[44:45], 0, v[188:189]
	global_load_lds_dwordx4 v[194:195], off
	s_setprio 1
	s_waitcnt lgkmcnt(0)
	s_barrier
; #define PG8_STAGE(bufoff, gbase, voff) do { _Pragma("unroll") for (int _i = 0; _i < 2; ++_i) \
;         __builtin_amdgcn_global_load_lds((const unsigned*)((const char*)(gbase) + (voff)[_i]), (LAS unsigned*)(lds + (bufoff) + ldsw + _i * 8192), 16, 0, 0); } while (0)
; #define PG8_LDA(dst, b, h) do { _Pragma("unroll") for (int m = 0; m < 4; ++m) _Pragma("unroll") for (int k = 0; k < 2; ++k) dst[m][k] = *(const LAS bf16x8*)(lds + PG8_SA(b, h) + aoff + m * 2048 + k * 1024); } while (0)
; #define PG8_MMA(ai, bj, At, Bt) do { __builtin_amdgcn_s_setprio(1); _Pragma("unroll") for (int m = 0; m < 4; ++m) _Pragma("unroll") for (int n = 0; n < 2; ++n) _Pragma("unroll") for (int k = 0; k < 2; ++k) \
;         acc[ai][bj][m][n] = __builtin_amdgcn_mfma_f32_16x16x32_bf16(Bt[n][k], At[m][k], acc[ai][bj][m][n], 0, 0, 0); __builtin_amdgcn_s_setprio(0); } while (0)
; #define PG8_WAIT_V(n) asm volatile("s_waitcnt vmcnt(" #n ")" ::: "memory")
; #define PG8_WAIT_L(n) asm volatile("s_waitcnt lgkmcnt(" #n ")" ::: "memory")
; #define PG8_BAR __builtin_amdgcn_s_barrier()
; #define PG8_SCHED __builtin_amdgcn_sched_barrier(0)
; template <class Epi, int AMODE>
; __device__ __forceinline__ void gemm_phase(LAS unsigned char* lds, const Gemm g, const StaticOrder& S, const Epi& E, int stagger_us, int tid_in) {
;     ...
;             PG8_WAIT_V(8); PG8_WAIT_L(0); PG8_BAR; PG8_MMA(0, 0, At, B0); PG8_MMA(0, 1, At, B1); PG8_BAR; PG8_SCHED;
;             PG8_LDA(At, 0, 1); PG8_STAGE(PG8_SB(0, 0), b2, voffB); PG8_STAGE(PG8_SB(0, 1), b2 + hstepB, voffB); PG8_STAGE(PG8_SA(0, 0), a2, voffA);
;             PG8_WAIT_V(8); PG8_WAIT_L(0); PG8_BAR; PG8_MMA(1, 0, At, B0); PG8_MMA(1, 1, At, B1); PG8_BAR; PG8_SCHED;
	v_mfma_f32_16x16x32_bf16 v[126:129], v[130:133], v[162:165], v[126:129]
	v_mfma_f32_16x16x32_bf16 v[122:125], v[138:141], v[162:165], v[122:125]
	v_mfma_f32_16x16x32_bf16 v[118:121], v[130:133], v[170:173], v[118:121]
	v_mfma_f32_16x16x32_bf16 v[114:117], v[138:141], v[170:173], v[114:117]
	v_mfma_f32_16x16x32_bf16 v[110:113], v[130:133], v[190:193], v[110:113]
	v_mfma_f32_16x16x32_bf16 v[102:105], v[138:141], v[190:193], v[102:105]
	v_mfma_f32_16x16x32_bf16 v[90:93], v[130:133], v[206:209], v[90:93]
	v_mfma_f32_16x16x32_bf16 v[82:85], v[138:141], v[206:209], v[82:85]
	v_mfma_f32_16x16x32_bf16 v[126:129], v[134:137], v[166:169], v[126:129]
	v_mfma_f32_16x16x32_bf16 v[122:125], v[142:145], v[166:169], v[122:125]
	v_mfma_f32_16x16x32_bf16 v[118:121], v[134:137], v[174:177], v[118:121]
	v_mfma_f32_16x16x32_bf16 v[114:117], v[142:145], v[174:177], v[114:117]
	v_mfma_f32_16x16x32_bf16 v[110:113], v[134:137], v[202:205], v[110:113]
	v_mfma_f32_16x16x32_bf16 v[102:105], v[142:145], v[202:205], v[102:105]
	v_mfma_f32_16x16x32_bf16 v[90:93], v[134:137], v[210:213], v[90:93]
	v_mfma_f32_16x16x32_bf16 v[82:85], v[142:145], v[210:213], v[82:85]
	v_mfma_f32_16x16x32_bf16 v[106:109], v[146:149], v[162:165], v[106:109]
	v_mfma_f32_16x16x32_bf16 v[98:101], v[154:157], v[162:165], v[98:101]
	v_mfma_f32_16x16x32_bf16 v[94:97], v[146:149], v[170:173], v[94:97]
	v_mfma_f32_16x16x32_bf16 v[86:89], v[154:157], v[170:173], v[86:89]
	v_mfma_f32_16x16x32_bf16 v[70:73], v[146:149], v[190:193], v[70:73]
	v_mfma_f32_16x16x32_bf16 v[62:65], v[154:157], v[190:193], v[62:65]
	v_mfma_f32_16x16x32_bf16 v[78:81], v[146:149], v[206:209], v[78:81]
	v_mfma_f32_16x16x32_bf16 v[66:69], v[154:157], v[206:209], v[66:69]
	v_mfma_f32_16x16x32_bf16 v[106:109], v[150:153], v[166:169], v[106:109]
	v_mfma_f32_16x16x32_bf16 v[98:101], v[158:161], v[166:169], v[98:101]
	v_mfma_f32_16x16x32_bf16 v[94:97], v[150:153], v[174:177], v[94:97]
	v_mfma_f32_16x16x32_bf16 v[86:89], v[158:161], v[174:177], v[86:89]
	v_mfma_f32_16x16x32_bf16 v[70:73], v[150:153], v[202:205], v[70:73]
	v_mfma_f32_16x16x32_bf16 v[62:65], v[158:161], v[202:205], v[62:65]
	v_mfma_f32_16x16x32_bf16 v[78:81], v[150:153], v[210:213], v[78:81]
	v_mfma_f32_16x16x32_bf16 v[66:69], v[158:161], v[210:213], v[66:69]
	s_setprio 0
	s_barrier
	s_add_i32 s34, s34, s91
	v_lshl_add_u64 v[194:195], s[6:7], 0, v[0:1]
	s_mov_b32 m0, s34
	ds_read_b128 v[162:165], v201 offset:16384
	ds_read_b128 v[166:169], v201 offset:17408
	ds_read_b128 v[170:173], v201 offset:18432
	ds_read_b128 v[174:177], v201 offset:19456
	ds_read_b128 v[190:193], v201 offset:20480
	ds_read_b128 v[202:205], v201 offset:21504
	ds_read_b128 v[206:209], v201 offset:22528
	ds_read_b128 v[210:213], v201 offset:23552
	global_load_lds_dwordx4 v[194:195], off
	s_add_i32 m0, s34, 0x2000
	s_add_u32 s44, s6, 0x80000
	v_lshl_add_u64 v[214:215], s[6:7], 0, v[182:183]
	s_addc_u32 s45, s7, 0
	s_add_i32 s34, s35, s91
	global_load_lds_dwordx4 v[214:215], off
	v_lshl_add_u64 v[216:217], s[44:45], 0, v[0:1]
	s_mov_b32 m0, s34
	v_lshl_add_u64 v[218:219], s[42:43], 0, v[180:181]
	global_load_lds_dwordx4 v[216:217], off
	s_add_i32 m0, s34, 0x2000
	v_lshl_add_u64 v[216:217], s[44:45], 0, v[182:183]
	global_load_lds_dwordx4 v[216:217], off
	s_mov_b32 m0, s93
	v_lshl_add_u64 v[216:217], s[42:43], 0, v[178:179]
	global_load_lds_dwordx4 v[216:217], off
	s_mov_b32 m0, s83
	s_nop 0
	global_load_lds_dwordx4 v[218:219], off
	s_setprio 1
	s_waitcnt lgkmcnt(0)
	s_barrier
	v_mfma_f32_16x16x32_bf16 v[54:57], v[130:133], v[162:165], v[54:57]
	v_mfma_f32_16x16x32_bf16 v[46:49], v[138:141], v[162:165], v[46:49]
	v_mfma_f32_16x16x32_bf16 v[38:41], v[130:133], v[170:173], v[38:41]
	v_mfma_f32_16x16x32_bf16 v[50:53], v[138:141], v[170:173], v[50:53]
	v_mfma_f32_16x16x32_bf16 v[18:21], v[130:133], v[190:193], v[18:21]
	v_mfma_f32_16x16x32_bf16 v[34:37], v[138:141], v[190:193], v[34:37]
	v_mfma_f32_16x16x32_bf16 v[22:25], v[130:133], v[206:209], v[22:25]
	v_mfma_f32_16x16x32_bf16 v[74:77], v[138:141], v[206:209], v[74:77]
	v_mfma_f32_16x16x32_bf16 v[54:57], v[134:137], v[166:169], v[54:57]
	v_mfma_f32_16x16x32_bf16 v[46:49], v[142:145], v[166:169], v[46:49]
	v_mfma_f32_16x16x32_bf16 v[38:41], v[134:137], v[174:177], v[38:41]
	v_mfma_f32_16x16x32_bf16 v[50:53], v[142:145], v[174:177], v[50:53]
	v_mfma_f32_16x16x32_bf16 v[18:21], v[134:137], v[202:205], v[18:21]
	v_mfma_f32_16x16x32_bf16 v[34:37], v[142:145], v[202:205], v[34:37]
	v_mfma_f32_16x16x32_bf16 v[22:25], v[134:137], v[210:213], v[22:25]
	v_mfma_f32_16x16x32_bf16 v[74:77], v[142:145], v[210:213], v[74:77]
	v_mfma_f32_16x16x32_bf16 v[58:61], v[146:149], v[162:165], v[58:61]
	v_mfma_f32_16x16x32_bf16 v[30:33], v[154:157], v[162:165], v[30:33]
	v_mfma_f32_16x16x32_bf16 v[42:45], v[146:149], v[170:173], v[42:45]
	v_mfma_f32_16x16x32_bf16 v[6:9], v[154:157], v[170:173], v[6:9]
	v_mfma_f32_16x16x32_bf16 v[26:29], v[146:149], v[190:193], v[26:29]
	v_mfma_f32_16x16x32_bf16 v[10:13], v[154:157], v[190:193], v[10:13]
	v_mfma_f32_16x16x32_bf16 v[14:17], v[146:149], v[206:209], v[14:17]
	v_mfma_f32_16x16x32_bf16 v[2:5], v[154:157], v[206:209], v[2:5]
	v_mfma_f32_16x16x32_bf16 v[58:61], v[150:153], v[166:169], v[58:61]
	v_mfma_f32_16x16x32_bf16 v[30:33], v[158:161], v[166:169], v[30:33]
	v_mfma_f32_16x16x32_bf16 v[42:45], v[150:153], v[174:177], v[42:45]
	v_mfma_f32_16x16x32_bf16 v[6:9], v[158:161], v[174:177], v[6:9]
	v_mfma_f32_16x16x32_bf16 v[26:29], v[150:153], v[202:205], v[26:29]
	v_mfma_f32_16x16x32_bf16 v[10:13], v[158:161], v[202:205], v[10:13]
	v_mfma_f32_16x16x32_bf16 v[14:17], v[150:153], v[210:213], v[14:17]
	v_mfma_f32_16x16x32_bf16 v[2:5], v[158:161], v[210:213], v[2:5]
	s_setprio 0
	s_barrier
; #define PG8_STAGE(bufoff, gbase, voff) do { _Pragma("unroll") for (int _i = 0; _i < 2; ++_i) \
;         __builtin_amdgcn_global_load_lds((const unsigned*)((const char*)(gbase) + (voff)[_i]), (LAS unsigned*)(lds + (bufoff) + ldsw + _i * 8192), 16, 0, 0); } while (0)
; #define PG8_LDA(dst, b, h) do { _Pragma("unroll") for (int m = 0; m < 4; ++m) _Pragma("unroll") for (int k = 0; k < 2; ++k) dst[m][k] = *(const LAS bf16x8*)(lds + PG8_SA(b, h) + aoff + m * 2048 + k * 1024); } while (0)
; #define PG8_LDB(dst, b, h) do { _Pragma("unroll") for (int n = 0; n < 2; ++n) _Pragma("unroll") for (int k = 0; k < 2; ++k) dst[n][k] = *(const LAS bf16x8*)(lds + PG8_SB(b, h) + boff + n * 2048 + k * 1024); } while (0)
; #define PG8_MMA(ai, bj, At, Bt) do { __builtin_amdgcn_s_setprio(1); _Pragma("unroll") for (int m = 0; m < 4; ++m) _Pragma("unroll") for (int n = 0; n < 2; ++n) _Pragma("unroll") for (int k = 0; k < 2; ++k) \
;         acc[ai][bj][m][n] = __builtin_amdgcn_mfma_f32_16x16x32_bf16(Bt[n][k], At[m][k], acc[ai][bj][m][n], 0, 0, 0); __builtin_amdgcn_s_setprio(0); } while (0)
; #define PG8_WAIT_V(n) asm volatile("s_waitcnt vmcnt(" #n ")" ::: "memory")
; #define PG8_WAIT_L(n) asm volatile("s_waitcnt lgkmcnt(" #n ")" ::: "memory")
; #define PG8_BAR __builtin_amdgcn_s_barrier()
; #define PG8_SCHED __builtin_amdgcn_sched_barrier(0)
; template <class Epi, int AMODE>
; __device__ __forceinline__ void gemm_phase(LAS unsigned char* lds, const Gemm g, const StaticOrder& S, const Epi& E, int stagger_us, int tid_in) {
;     ...
;             PG8_LDB(B0, 1, 0); PG8_LDB(B1, 1, 1); PG8_SCHED; PG8_LDA(At, 1, 0); PG8_STAGE(PG8_SA(0, 1), a2 + hstepA, voffA);
;             PG8_WAIT_V(8); PG8_WAIT_L(0); PG8_BAR; PG8_MMA(0, 0, At, B0); PG8_MMA(0, 1, At, B1); PG8_BAR; PG8_SCHED;
;             PG8_LDA(At, 1, 1); PG8_STAGE(PG8_SB(1, 0), b3, voffB); PG8_STAGE(PG8_SB(1, 1), b3 + hstepB, voffB); PG8_STAGE(PG8_SA(1, 0), a3, voffA);
;             PG8_WAIT_V(8); PG8_WAIT_L(0); PG8_BAR; PG8_MMA(1, 0, At, B0); PG8_MMA(1, 1, At, B1); PG8_BAR; PG8_SCHED;
	s_add_i32 s34, 0, 0x18000
	s_add_i32 s35, 0, 0x1c000
	v_add_u32_e32 v142, s34, v196
	v_add_u32_e32 v158, s35, v196
	ds_read_b128 v[130:133], v142
	ds_read_b128 v[134:137], v142 offset:1024
	ds_read_b128 v[138:141], v142 offset:2048
	ds_read_b128 v[142:145], v142 offset:3072
	ds_read_b128 v[146:149], v158
	ds_read_b128 v[150:153], v158 offset:1024
	ds_read_b128 v[154:157], v158 offset:2048
	ds_read_b128 v[158:161], v158 offset:3072
	s_add_u32 s42, s42, 0x4000
	s_addc_u32 s43, s43, 0
	s_mov_b32 m0, s79
	v_lshl_add_u64 v[220:221], s[42:43], 0, v[178:179]
	ds_read_b128 v[162:165], v201 offset:32768
	ds_read_b128 v[166:169], v201 offset:33792
	ds_read_b128 v[170:173], v201 offset:34816
	ds_read_b128 v[174:177], v201 offset:35840
	ds_read_b128 v[190:193], v201 offset:36864
	ds_read_b128 v[202:205], v201 offset:37888
	ds_read_b128 v[206:209], v201 offset:38912
	ds_read_b128 v[210:213], v201 offset:39936
	global_load_lds_dwordx4 v[220:221], off
	s_mov_b32 m0, s87
	v_lshl_add_u64 v[220:221], s[42:43], 0, v[180:181]
	global_load_lds_dwordx4 v[220:221], off
	s_setprio 1
	s_waitcnt vmcnt(8) lgkmcnt(0)
	s_barrier
	v_mfma_f32_16x16x32_bf16 v[126:129], v[130:133], v[162:165], v[126:129]
	v_mfma_f32_16x16x32_bf16 v[122:125], v[138:141], v[162:165], v[122:125]
	v_mfma_f32_16x16x32_bf16 v[118:121], v[130:133], v[170:173], v[118:121]
	v_mfma_f32_16x16x32_bf16 v[114:117], v[138:141], v[170:173], v[114:117]
	v_mfma_f32_16x16x32_bf16 v[110:113], v[130:133], v[190:193], v[110:113]
	v_mfma_f32_16x16x32_bf16 v[102:105], v[138:141], v[190:193], v[102:105]
	v_mfma_f32_16x16x32_bf16 v[90:93], v[130:133], v[206:209], v[90:93]
	v_mfma_f32_16x16x32_bf16 v[82:85], v[138:141], v[206:209], v[82:85]
	v_mfma_f32_16x16x32_bf16 v[126:129], v[134:137], v[166:169], v[126:129]
	v_mfma_f32_16x16x32_bf16 v[122:125], v[142:145], v[166:169], v[122:125]
	v_mfma_f32_16x16x32_bf16 v[118:121], v[134:137], v[174:177], v[118:121]
	v_mfma_f32_16x16x32_bf16 v[114:117], v[142:145], v[174:177], v[114:117]
	v_mfma_f32_16x16x32_bf16 v[110:113], v[134:137], v[202:205], v[110:113]
	v_mfma_f32_16x16x32_bf16 v[102:105], v[142:145], v[202:205], v[102:105]
	v_mfma_f32_16x16x32_bf16 v[90:93], v[134:137], v[210:213], v[90:93]
	v_mfma_f32_16x16x32_bf16 v[82:85], v[142:145], v[210:213], v[82:85]
	v_mfma_f32_16x16x32_bf16 v[106:109], v[146:149], v[162:165], v[106:109]
	v_mfma_f32_16x16x32_bf16 v[98:101], v[154:157], v[162:165], v[98:101]
	v_mfma_f32_16x16x32_bf16 v[94:97], v[146:149], v[170:173], v[94:97]
	v_mfma_f32_16x16x32_bf16 v[86:89], v[154:157], v[170:173], v[86:89]
	v_mfma_f32_16x16x32_bf16 v[70:73], v[146:149], v[190:193], v[70:73]
	v_mfma_f32_16x16x32_bf16 v[62:65], v[154:157], v[190:193], v[62:65]
	v_mfma_f32_16x16x32_bf16 v[78:81], v[146:149], v[206:209], v[78:81]
	v_mfma_f32_16x16x32_bf16 v[66:69], v[154:157], v[206:209], v[66:69]
	v_mfma_f32_16x16x32_bf16 v[106:109], v[150:153], v[166:169], v[106:109]
	v_mfma_f32_16x16x32_bf16 v[98:101], v[158:161], v[166:169], v[98:101]
	v_mfma_f32_16x16x32_bf16 v[94:97], v[150:153], v[174:177], v[94:97]
	v_mfma_f32_16x16x32_bf16 v[86:89], v[158:161], v[174:177], v[86:89]
	v_mfma_f32_16x16x32_bf16 v[70:73], v[150:153], v[202:205], v[70:73]
	v_mfma_f32_16x16x32_bf16 v[62:65], v[158:161], v[202:205], v[62:65]
	v_mfma_f32_16x16x32_bf16 v[78:81], v[150:153], v[210:213], v[78:81]
	v_mfma_f32_16x16x32_bf16 v[66:69], v[158:161], v[210:213], v[66:69]
	s_setprio 0
	s_barrier
	s_add_i32 s34, s34, s91
	v_lshl_add_u64 v[194:195], v[194:195], 0, s[74:75]
	s_mov_b32 m0, s34
	ds_read_b128 v[162:165], v201 offset:49152
	ds_read_b128 v[166:169], v201 offset:50176
	ds_read_b128 v[170:173], v201 offset:51200
	ds_read_b128 v[174:177], v201 offset:52224
	ds_read_b128 v[190:193], v201 offset:53248
	ds_read_b128 v[202:205], v201 offset:54272
	ds_read_b128 v[206:209], v201 offset:55296
	ds_read_b128 v[210:213], v201 offset:56320
	global_load_lds_dwordx4 v[194:195], off
	s_add_i32 m0, s34, 0x2000
	s_add_u32 s6, s6, 0x80080
	v_lshl_add_u64 v[194:195], v[214:215], 0, s[74:75]
	s_addc_u32 s7, s7, 0
	s_add_i32 s34, s35, s91
	global_load_lds_dwordx4 v[194:195], off
	s_mov_b32 m0, s34
	v_lshl_add_u64 v[194:195], s[6:7], 0, v[0:1]
	global_load_lds_dwordx4 v[194:195], off
	s_add_i32 m0, s34, 0x2000
	v_lshl_add_u64 v[194:195], s[6:7], 0, v[182:183]
	global_load_lds_dwordx4 v[194:195], off
	s_mov_b32 m0, s67
	v_lshl_add_u64 v[194:195], v[216:217], 0, s[74:75]
	global_load_lds_dwordx4 v[194:195], off
	s_mov_b32 m0, s85
	v_lshl_add_u64 v[194:195], v[218:219], 0, s[74:75]
	global_load_lds_dwordx4 v[194:195], off
	s_setprio 1
	s_waitcnt vmcnt(8) lgkmcnt(0)
	s_barrier
	v_mfma_f32_16x16x32_bf16 v[54:57], v[130:133], v[162:165], v[54:57]
	v_mfma_f32_16x16x32_bf16 v[46:49], v[138:141], v[162:165], v[46:49]
	v_mfma_f32_16x16x32_bf16 v[38:41], v[130:133], v[170:173], v[38:41]
	v_mfma_f32_16x16x32_bf16 v[50:53], v[138:141], v[170:173], v[50:53]
	v_mfma_f32_16x16x32_bf16 v[18:21], v[130:133], v[190:193], v[18:21]
	v_mfma_f32_16x16x32_bf16 v[34:37], v[138:141], v[190:193], v[34:37]
	v_mfma_f32_16x16x32_bf16 v[22:25], v[130:133], v[206:209], v[22:25]
	v_mfma_f32_16x16x32_bf16 v[74:77], v[138:141], v[206:209], v[74:77]
	v_mfma_f32_16x16x32_bf16 v[54:57], v[134:137], v[166:169], v[54:57]
	v_mfma_f32_16x16x32_bf16 v[46:49], v[142:145], v[166:169], v[46:49]
	v_mfma_f32_16x16x32_bf16 v[38:41], v[134:137], v[174:177], v[38:41]
	v_mfma_f32_16x16x32_bf16 v[50:53], v[142:145], v[174:177], v[50:53]
	v_mfma_f32_16x16x32_bf16 v[18:21], v[134:137], v[202:205], v[18:21]
	v_mfma_f32_16x16x32_bf16 v[34:37], v[142:145], v[202:205], v[34:37]
	v_mfma_f32_16x16x32_bf16 v[22:25], v[134:137], v[210:213], v[22:25]
	v_mfma_f32_16x16x32_bf16 v[74:77], v[142:145], v[210:213], v[74:77]
	v_mfma_f32_16x16x32_bf16 v[58:61], v[146:149], v[162:165], v[58:61]
	v_mfma_f32_16x16x32_bf16 v[30:33], v[154:157], v[162:165], v[30:33]
	v_mfma_f32_16x16x32_bf16 v[42:45], v[146:149], v[170:173], v[42:45]
	v_mfma_f32_16x16x32_bf16 v[6:9], v[154:157], v[170:173], v[6:9]
	v_mfma_f32_16x16x32_bf16 v[26:29], v[146:149], v[190:193], v[26:29]
	v_mfma_f32_16x16x32_bf16 v[10:13], v[154:157], v[190:193], v[10:13]
	v_mfma_f32_16x16x32_bf16 v[14:17], v[146:149], v[206:209], v[14:17]
	v_mfma_f32_16x16x32_bf16 v[2:5], v[154:157], v[206:209], v[2:5]
	v_mfma_f32_16x16x32_bf16 v[58:61], v[150:153], v[166:169], v[58:61]
	v_mfma_f32_16x16x32_bf16 v[30:33], v[158:161], v[166:169], v[30:33]
	v_mfma_f32_16x16x32_bf16 v[42:45], v[150:153], v[174:177], v[42:45]
	v_mfma_f32_16x16x32_bf16 v[6:9], v[158:161], v[174:177], v[6:9]
	v_mfma_f32_16x16x32_bf16 v[26:29], v[150:153], v[202:205], v[26:29]
	v_mfma_f32_16x16x32_bf16 v[10:13], v[158:161], v[202:205], v[10:13]
	v_mfma_f32_16x16x32_bf16 v[14:17], v[150:153], v[210:213], v[14:17]
	v_mfma_f32_16x16x32_bf16 v[2:5], v[158:161], v[210:213], v[2:5]
	s_setprio 0
	s_barrier
	s_add_i32 s31, s31, 2
	s_add_u32 s29, s29, 0x100
	s_addc_u32 s30, s30, 0
	s_cmp_gt_u32 s31, 29
	s_mov_b64 s[44:45], s[4:5]
	.p2align	6

; template <class Epi, int AMODE>
; __device__ __forceinline__ void gemm_phase(LAS unsigned char* lds, const Gemm g, const StaticOrder& S, const Epi& E, int stagger_us, int tid_in) {
;     ...
;         for (int t = 0; t < nt; t += 2) {
;             const bool last = (t == nt - 2);
;             const char* a1 = cA + (size_t)(t + 1) * kstep;
;             const char* a2 = last ? nA : cA + (size_t)(t + 2) * kstep; const char* b2 = last ? nB : cB + (size_t)(t + 2) * kstep;
;             const char* a3 = a2 + kstep; const char* b3 = b2 + kstep;
;     ...
;         for (int a = 0; a < 2; ++a)
; #pragma unroll
;             for (int b = 0; b < 2; ++b)
; #pragma unroll
;                 for (int m = 0; m < 4; ++m)
; #pragma unroll
;                     for (int n = 0; n < 2; ++n) acc[a][b][m][n] = (f32x4){0.f, 0.f, 0.f, 0.f};
.LBB0_1475:
	s_add_u32 s27, s4, 0x100
	v_mov_b32_e32 v2, 0
	s_addc_u32 s28, s5, 0
	s_mov_b32 s29, -2
	v_mov_b32_e32 v3, v2
	v_mov_b32_e32 v4, v2
	v_mov_b32_e32 v5, v2
	v_mov_b32_e32 v6, v2
	v_mov_b32_e32 v7, v2
	v_mov_b32_e32 v8, v2
	v_mov_b32_e32 v9, v2
	v_mov_b32_e32 v14, v2
	v_mov_b32_e32 v15, v2
	v_mov_b32_e32 v16, v2
	v_mov_b32_e32 v17, v2
	v_mov_b32_e32 v18, v2
	v_mov_b32_e32 v19, v2
	v_mov_b32_e32 v20, v2
	v_mov_b32_e32 v21, v2
	v_mov_b32_e32 v34, v2
	v_mov_b32_e32 v35, v2
	v_mov_b32_e32 v36, v2
	v_mov_b32_e32 v37, v2
	v_mov_b32_e32 v38, v2
	v_mov_b32_e32 v39, v2
	v_mov_b32_e32 v40, v2
	v_mov_b32_e32 v41, v2
	v_mov_b32_e32 v42, v2
	v_mov_b32_e32 v43, v2
	v_mov_b32_e32 v44, v2
	v_mov_b32_e32 v45, v2
	v_mov_b32_e32 v46, v2
	v_mov_b32_e32 v47, v2
	v_mov_b32_e32 v48, v2
	v_mov_b32_e32 v49, v2
	v_mov_b32_e32 v10, v2
	v_mov_b32_e32 v11, v2
	v_mov_b32_e32 v12, v2
	v_mov_b32_e32 v13, v2
	v_mov_b32_e32 v22, v2
	v_mov_b32_e32 v23, v2
	v_mov_b32_e32 v24, v2
	v_mov_b32_e32 v25, v2
	v_mov_b32_e32 v26, v2
	v_mov_b32_e32 v27, v2
	v_mov_b32_e32 v28, v2
	v_mov_b32_e32 v29, v2
	v_mov_b32_e32 v30, v2
	v_mov_b32_e32 v31, v2
	v_mov_b32_e32 v32, v2
	v_mov_b32_e32 v33, v2
	v_mov_b32_e32 v50, v2
	v_mov_b32_e32 v51, v2
	v_mov_b32_e32 v52, v2
	v_mov_b32_e32 v53, v2
	v_mov_b32_e32 v54, v2
	v_mov_b32_e32 v55, v2
	v_mov_b32_e32 v56, v2
	v_mov_b32_e32 v57, v2
	v_mov_b32_e32 v58, v2
	v_mov_b32_e32 v59, v2
	v_mov_b32_e32 v60, v2
	v_mov_b32_e32 v61, v2
	v_mov_b32_e32 v62, v2
	v_mov_b32_e32 v63, v2
	v_mov_b32_e32 v64, v2
	v_mov_b32_e32 v65, v2
	v_mov_b32_e32 v78, v2
	v_mov_b32_e32 v79, v2
	v_mov_b32_e32 v80, v2
	v_mov_b32_e32 v81, v2
	v_mov_b32_e32 v82, v2
	v_mov_b32_e32 v83, v2
	v_mov_b32_e32 v84, v2
	v_mov_b32_e32 v85, v2
	v_mov_b32_e32 v86, v2
	v_mov_b32_e32 v87, v2
	v_mov_b32_e32 v88, v2
	v_mov_b32_e32 v89, v2
	v_mov_b32_e32 v90, v2
	v_mov_b32_e32 v91, v2
	v_mov_b32_e32 v92, v2
	v_mov_b32_e32 v93, v2
	v_mov_b32_e32 v114, v2
	v_mov_b32_e32 v115, v2
	v_mov_b32_e32 v116, v2
	v_mov_b32_e32 v117, v2
	v_mov_b32_e32 v118, v2
	v_mov_b32_e32 v119, v2
	v_mov_b32_e32 v120, v2
	v_mov_b32_e32 v121, v2
	v_mov_b32_e32 v122, v2
	v_mov_b32_e32 v123, v2
	v_mov_b32_e32 v124, v2
	v_mov_b32_e32 v125, v2
	v_mov_b32_e32 v126, v2
	v_mov_b32_e32 v127, v2
	v_mov_b32_e32 v128, v2
	v_mov_b32_e32 v129, v2
	v_mov_b32_e32 v94, v2
	v_mov_b32_e32 v95, v2
	v_mov_b32_e32 v96, v2
	v_mov_b32_e32 v97, v2
	v_mov_b32_e32 v98, v2
	v_mov_b32_e32 v99, v2
	v_mov_b32_e32 v100, v2
	v_mov_b32_e32 v101, v2
	v_mov_b32_e32 v106, v2
	v_mov_b32_e32 v107, v2
	v_mov_b32_e32 v108, v2
	v_mov_b32_e32 v109, v2
	v_mov_b32_e32 v110, v2
	v_mov_b32_e32 v111, v2
	v_mov_b32_e32 v112, v2
	v_mov_b32_e32 v113, v2
	v_mov_b32_e32 v130, v2
	v_mov_b32_e32 v131, v2
	v_mov_b32_e32 v132, v2
	v_mov_b32_e32 v133, v2
	v_mov_b32_e32 v134, v2
	v_mov_b32_e32 v135, v2
	v_mov_b32_e32 v136, v2
	v_mov_b32_e32 v137, v2
	v_mov_b32_e32 v138, v2
	v_mov_b32_e32 v139, v2
	v_mov_b32_e32 v140, v2
	v_mov_b32_e32 v141, v2
	v_mov_b32_e32 v142, v2
	v_mov_b32_e32 v143, v2
	v_mov_b32_e32 v144, v2
	v_mov_b32_e32 v145, v2
	.p2align	6

; template <class Epi, int AMODE>
; __device__ __forceinline__ void gemm_phase(LAS unsigned char* lds, const Gemm g, const StaticOrder& S, const Epi& E, int stagger_us, int tid_in) {
;     ...
;         for (int t = 0; t < nt; t += 2) {
;             const bool last = (t == nt - 2);
;             const char* a1 = cA + (size_t)(t + 1) * kstep;
;             const char* a2 = last ? nA : cA + (size_t)(t + 2) * kstep; const char* b2 = last ? nB : cB + (size_t)(t + 2) * kstep;
;             const char* a3 = a2 + kstep; const char* b3 = b2 + kstep;
;     ...
;         for (int a = 0; a < 2; ++a)
; #pragma unroll
;             for (int b = 0; b < 2; ++b)
; #pragma unroll
;                 for (int m = 0; m < 4; ++m)
; #pragma unroll
;                     for (int n = 0; n < 2; ++n) acc[a][b][m][n] = (f32x4){0.f, 0.f, 0.f, 0.f};
.LBB0_1497:
	s_add_u32 s27, s4, 0x100
	v_mov_b32_e32 v2, 0
	s_addc_u32 s28, s5, 0
	s_mov_b32 s29, -2
	v_mov_b32_e32 v3, v2
	v_mov_b32_e32 v4, v2
	v_mov_b32_e32 v5, v2
	v_mov_b32_e32 v6, v2
	v_mov_b32_e32 v7, v2
	v_mov_b32_e32 v8, v2
	v_mov_b32_e32 v9, v2
	v_mov_b32_e32 v18, v2
	v_mov_b32_e32 v19, v2
	v_mov_b32_e32 v20, v2
	v_mov_b32_e32 v21, v2
	v_mov_b32_e32 v22, v2
	v_mov_b32_e32 v23, v2
	v_mov_b32_e32 v24, v2
	v_mov_b32_e32 v25, v2
	v_mov_b32_e32 v34, v2
	v_mov_b32_e32 v35, v2
	v_mov_b32_e32 v36, v2
	v_mov_b32_e32 v37, v2
	v_mov_b32_e32 v38, v2
	v_mov_b32_e32 v39, v2
	v_mov_b32_e32 v40, v2
	v_mov_b32_e32 v41, v2
	v_mov_b32_e32 v66, v2
	v_mov_b32_e32 v67, v2
	v_mov_b32_e32 v68, v2
	v_mov_b32_e32 v69, v2
	v_mov_b32_e32 v70, v2
	v_mov_b32_e32 v71, v2
	v_mov_b32_e32 v72, v2
	v_mov_b32_e32 v73, v2
	v_mov_b32_e32 v10, v2
	v_mov_b32_e32 v11, v2
	v_mov_b32_e32 v12, v2
	v_mov_b32_e32 v13, v2
	v_mov_b32_e32 v14, v2
	v_mov_b32_e32 v15, v2
	v_mov_b32_e32 v16, v2
	v_mov_b32_e32 v17, v2
	v_mov_b32_e32 v26, v2
	v_mov_b32_e32 v27, v2
	v_mov_b32_e32 v28, v2
	v_mov_b32_e32 v29, v2
	v_mov_b32_e32 v30, v2
	v_mov_b32_e32 v31, v2
	v_mov_b32_e32 v32, v2
	v_mov_b32_e32 v33, v2
	v_mov_b32_e32 v42, v2
	v_mov_b32_e32 v43, v2
	v_mov_b32_e32 v44, v2
	v_mov_b32_e32 v45, v2
	v_mov_b32_e32 v46, v2
	v_mov_b32_e32 v47, v2
	v_mov_b32_e32 v48, v2
	v_mov_b32_e32 v49, v2
	v_mov_b32_e32 v74, v2
	v_mov_b32_e32 v75, v2
	v_mov_b32_e32 v76, v2
	v_mov_b32_e32 v77, v2
	v_mov_b32_e32 v78, v2
	v_mov_b32_e32 v79, v2
	v_mov_b32_e32 v80, v2
	v_mov_b32_e32 v81, v2
	v_mov_b32_e32 v82, v2
	v_mov_b32_e32 v83, v2
	v_mov_b32_e32 v84, v2
	v_mov_b32_e32 v85, v2
	v_mov_b32_e32 v86, v2
	v_mov_b32_e32 v87, v2
	v_mov_b32_e32 v88, v2
	v_mov_b32_e32 v89, v2
	v_mov_b32_e32 v98, v2
	v_mov_b32_e32 v99, v2
	v_mov_b32_e32 v100, v2
	v_mov_b32_e32 v101, v2
	v_mov_b32_e32 v102, v2
	v_mov_b32_e32 v103, v2
	v_mov_b32_e32 v104, v2
	v_mov_b32_e32 v105, v2
	v_mov_b32_e32 v114, v2
	v_mov_b32_e32 v115, v2
	v_mov_b32_e32 v116, v2
	v_mov_b32_e32 v117, v2
	v_mov_b32_e32 v118, v2
	v_mov_b32_e32 v119, v2
	v_mov_b32_e32 v120, v2
	v_mov_b32_e32 v121, v2
	v_mov_b32_e32 v130, v2
	v_mov_b32_e32 v131, v2
	v_mov_b32_e32 v132, v2
	v_mov_b32_e32 v133, v2
	v_mov_b32_e32 v134, v2
	v_mov_b32_e32 v135, v2
	v_mov_b32_e32 v136, v2
	v_mov_b32_e32 v137, v2
	v_mov_b32_e32 v90, v2
	v_mov_b32_e32 v91, v2
	v_mov_b32_e32 v92, v2
	v_mov_b32_e32 v93, v2
	v_mov_b32_e32 v94, v2
	v_mov_b32_e32 v95, v2
	v_mov_b32_e32 v96, v2
	v_mov_b32_e32 v97, v2
	v_mov_b32_e32 v106, v2
	v_mov_b32_e32 v107, v2
	v_mov_b32_e32 v108, v2
	v_mov_b32_e32 v109, v2
	v_mov_b32_e32 v110, v2
	v_mov_b32_e32 v111, v2
	v_mov_b32_e32 v112, v2
	v_mov_b32_e32 v113, v2
	v_mov_b32_e32 v122, v2
	v_mov_b32_e32 v123, v2
	v_mov_b32_e32 v124, v2
	v_mov_b32_e32 v125, v2
	v_mov_b32_e32 v126, v2
	v_mov_b32_e32 v127, v2
	v_mov_b32_e32 v128, v2
	v_mov_b32_e32 v129, v2
	v_mov_b32_e32 v138, v2
	v_mov_b32_e32 v139, v2
	v_mov_b32_e32 v140, v2
	v_mov_b32_e32 v141, v2
	v_mov_b32_e32 v142, v2
	v_mov_b32_e32 v143, v2
	v_mov_b32_e32 v144, v2
	v_mov_b32_e32 v145, v2
	.p2align	6
